# opt13: + batched (32 in flight) loads in weight-transpose loops (p0a w_in, per-layer w_gate/w_up), rowwise late wait
# speedup vs baseline: 1.0237x; 1.0237x over previous
; #define LDS_WAIT() asm volatile("s_waitcnt lgkmcnt(0)" ::: "memory")
; template <bool KPERM = false, class SrcF>
; __device__ __forceinline__ void transpose_item(const float* W, int ldw, int K, half_t* WT, int nblk, float* scr, int item, int lane, SrcF src) {
;     ...
;     for (int i = 0; i < 32; ++i) { const int kk = 2 * i + (lane >> 5); scr[kk * 33 + (lane & 31)] = sc >= 0 ? W[(size_t)(k0 + (KPERM ? rope_perm(kk) : kk)) * ldw + sc] : 0.f; }
;     LDS_WAIT();
; __device__ __forceinline__ void phase_p0a(ArgsP a, unsigned char* lds) {
;     ...
;         if (r < DEPTH * I_IN) { const int l = r / I_IN; r %= I_IN; transpose_item(a->w_in + (size_t)l * D * NIN, NIN, D, wt_in + (size_t)l * NPROJ * D, NPROJ / 32, scr, r, lane, [](int p) { return win_src_col(p); }); continue; }
.LBB0_53:
	v_mov_b32_e32 v48, 0
	v_mov_b32_e32 v49, 0
	v_mov_b32_e32 v50, 0
	v_mov_b32_e32 v51, 0
	v_mov_b32_e32 v52, 0
	v_mov_b32_e32 v53, 0
	v_mov_b32_e32 v54, 0
	v_mov_b32_e32 v55, 0
	v_mov_b32_e32 v56, 0
	v_mov_b32_e32 v57, 0
	v_mov_b32_e32 v58, 0
	v_mov_b32_e32 v59, 0
	v_mov_b32_e32 v60, 0
	v_mov_b32_e32 v61, 0
	v_mov_b32_e32 v62, 0
	v_mov_b32_e32 v63, 0
	v_mov_b32_e32 v64, 0
	v_mov_b32_e32 v65, 0
	v_mov_b32_e32 v66, 0
	v_mov_b32_e32 v67, 0
	v_mov_b32_e32 v68, 0
	v_mov_b32_e32 v69, 0
	v_mov_b32_e32 v70, 0
	v_mov_b32_e32 v71, 0
	v_mov_b32_e32 v72, 0
	v_mov_b32_e32 v73, 0
	v_mov_b32_e32 v74, 0
	v_mov_b32_e32 v75, 0
	v_mov_b32_e32 v76, 0
	v_mov_b32_e32 v77, 0
	v_mov_b32_e32 v78, 0
	v_mov_b32_e32 v79, 0
	s_and_saveexec_b64 s[10:11], vcc
	s_cbranch_execz .Ltr53_w
	v_lshl_add_u64 v[46:47], v[24:25], 0, s[8:9]
	global_load_dword v48, v[46:47], off
	v_lshl_add_u64 v[46:47], v[22:23], 0, s[8:9]
	global_load_dword v49, v[46:47], off
	v_lshl_add_u64 v[46:47], v[20:21], 0, s[8:9]
	global_load_dword v50, v[46:47], off
	v_lshl_add_u64 v[46:47], v[18:19], 0, s[8:9]
	global_load_dword v51, v[46:47], off
	v_lshl_add_u64 v[46:47], v[16:17], 0, s[8:9]
	global_load_dword v52, v[46:47], off
	v_lshl_add_u64 v[46:47], v[14:15], 0, s[8:9]
	global_load_dword v53, v[46:47], off
	v_lshl_add_u64 v[46:47], v[12:13], 0, s[8:9]
	global_load_dword v54, v[46:47], off
	v_lshl_add_u64 v[46:47], v[10:11], 0, s[8:9]
	global_load_dword v55, v[46:47], off
	s_add_u32 s8, s8, 0x26300
	s_addc_u32 s9, s9, 0
	v_lshl_add_u64 v[46:47], v[24:25], 0, s[8:9]
	global_load_dword v56, v[46:47], off
	v_lshl_add_u64 v[46:47], v[22:23], 0, s[8:9]
	global_load_dword v57, v[46:47], off
	v_lshl_add_u64 v[46:47], v[20:21], 0, s[8:9]
	global_load_dword v58, v[46:47], off
	v_lshl_add_u64 v[46:47], v[18:19], 0, s[8:9]
	global_load_dword v59, v[46:47], off
	v_lshl_add_u64 v[46:47], v[16:17], 0, s[8:9]
	global_load_dword v60, v[46:47], off
	v_lshl_add_u64 v[46:47], v[14:15], 0, s[8:9]
	global_load_dword v61, v[46:47], off
	v_lshl_add_u64 v[46:47], v[12:13], 0, s[8:9]
	global_load_dword v62, v[46:47], off
	v_lshl_add_u64 v[46:47], v[10:11], 0, s[8:9]
	global_load_dword v63, v[46:47], off
	s_add_u32 s8, s8, 0x26300
	s_addc_u32 s9, s9, 0
	v_lshl_add_u64 v[46:47], v[24:25], 0, s[8:9]
	global_load_dword v64, v[46:47], off
	v_lshl_add_u64 v[46:47], v[22:23], 0, s[8:9]
	global_load_dword v65, v[46:47], off
	v_lshl_add_u64 v[46:47], v[20:21], 0, s[8:9]
	global_load_dword v66, v[46:47], off
	v_lshl_add_u64 v[46:47], v[18:19], 0, s[8:9]
	global_load_dword v67, v[46:47], off
	v_lshl_add_u64 v[46:47], v[16:17], 0, s[8:9]
	global_load_dword v68, v[46:47], off
	v_lshl_add_u64 v[46:47], v[14:15], 0, s[8:9]
	global_load_dword v69, v[46:47], off
	v_lshl_add_u64 v[46:47], v[12:13], 0, s[8:9]
	global_load_dword v70, v[46:47], off
	v_lshl_add_u64 v[46:47], v[10:11], 0, s[8:9]
	global_load_dword v71, v[46:47], off
	s_add_u32 s8, s8, 0x26300
	s_addc_u32 s9, s9, 0
	v_lshl_add_u64 v[46:47], v[24:25], 0, s[8:9]
	global_load_dword v72, v[46:47], off
	v_lshl_add_u64 v[46:47], v[22:23], 0, s[8:9]
	global_load_dword v73, v[46:47], off
	v_lshl_add_u64 v[46:47], v[20:21], 0, s[8:9]
	global_load_dword v74, v[46:47], off
	v_lshl_add_u64 v[46:47], v[18:19], 0, s[8:9]
	global_load_dword v75, v[46:47], off
	v_lshl_add_u64 v[46:47], v[16:17], 0, s[8:9]
	global_load_dword v76, v[46:47], off
	v_lshl_add_u64 v[46:47], v[14:15], 0, s[8:9]
	global_load_dword v77, v[46:47], off
	v_lshl_add_u64 v[46:47], v[12:13], 0, s[8:9]
	global_load_dword v78, v[46:47], off
	v_lshl_add_u64 v[46:47], v[10:11], 0, s[8:9]
	global_load_dword v79, v[46:47], off
.Ltr53_w:
	s_or_b64 exec, exec, s[10:11]
	s_waitcnt vmcnt(0)
	ds_write_b32 v3, v48
	ds_write_b32 v3, v49 offset:264
	ds_write_b32 v3, v50 offset:528
	ds_write_b32 v3, v51 offset:792
	ds_write_b32 v3, v52 offset:1056
	ds_write_b32 v3, v53 offset:1320
	ds_write_b32 v3, v54 offset:1584
	ds_write_b32 v3, v55 offset:1848
	ds_write_b32 v3, v56 offset:2112
	ds_write_b32 v3, v57 offset:2376
	ds_write_b32 v3, v58 offset:2640
	ds_write_b32 v3, v59 offset:2904
	ds_write_b32 v3, v60 offset:3168
	ds_write_b32 v3, v61 offset:3432
	ds_write_b32 v3, v62 offset:3696
	ds_write_b32 v3, v63 offset:3960
	ds_write_b32 v3, v64 offset:4224
	ds_write_b32 v3, v65 offset:4488
	ds_write_b32 v3, v66 offset:4752
	ds_write_b32 v3, v67 offset:5016
	ds_write_b32 v3, v68 offset:5280
	ds_write_b32 v3, v69 offset:5544
	ds_write_b32 v3, v70 offset:5808
	ds_write_b32 v3, v71 offset:6072
	ds_write_b32 v3, v72 offset:6336
	ds_write_b32 v3, v73 offset:6600
	ds_write_b32 v3, v74 offset:6864
	ds_write_b32 v3, v75 offset:7128
	ds_write_b32 v3, v76 offset:7392
	ds_write_b32 v3, v77 offset:7656
	ds_write_b32 v3, v78 offset:7920
	ds_write_b32 v3, v79 offset:8184
	s_branch .LBB0_19

; #define LDS_WAIT() asm volatile("s_waitcnt lgkmcnt(0)" ::: "memory")
; template <bool KPERM = false, class SrcF>
; __device__ __forceinline__ void transpose_item(const float* W, int ldw, int K, half_t* WT, int nblk, float* scr, int item, int lane, SrcF src) {
;     ...
;     for (int i = 0; i < 32; ++i) { const int kk = 2 * i + (lane >> 5); scr[kk * 33 + (lane & 31)] = sc >= 0 ? W[(size_t)(k0 + (KPERM ? rope_perm(kk) : kk)) * ldw + sc] : 0.f; }
;     LDS_WAIT();
; __device__ __forceinline__ void phase_compress(ArgsP a, int layer, unsigned char* lds) {
;     ...
;     for (int it = I.gw; it < 2 * I_G; it += I.NW) {
;         const int up = it >= I_G, r = up ? it - I_G : it, n0 = 32 * (r % (DFF / 32));
;         const long dsh = (long)(256 * (n0 >> 7) + (n0 & 127) + 128 * up) - n0;
;         transpose_item(up ? wu_ : wg, DFF, D, wt_gu + dsh * D, DFF / 32, scr, r, lane, [](int p) { return p; });
;     }
.LBB0_615:
	s_andn2_b64 vcc, exec, s[6:7]
	s_cbranch_vccnz .Ltr615_zero
	v_add_u32_e32 v96, 0, v0
	v_mad_i64_i32 v[98:99], s[18:19], v96, s89, v[4:5]
	global_load_dword v64, v[98:99], off
	v_add_u32_e32 v96, 2, v0
	v_mad_i64_i32 v[98:99], s[18:19], v96, s89, v[4:5]
	global_load_dword v65, v[98:99], off
	v_add_u32_e32 v96, 4, v0
	v_mad_i64_i32 v[98:99], s[18:19], v96, s89, v[4:5]
	global_load_dword v66, v[98:99], off
	v_add_u32_e32 v96, 6, v0
	v_mad_i64_i32 v[98:99], s[18:19], v96, s89, v[4:5]
	global_load_dword v67, v[98:99], off
	v_add_u32_e32 v96, 8, v0
	v_mad_i64_i32 v[98:99], s[18:19], v96, s89, v[4:5]
	global_load_dword v68, v[98:99], off
	v_add_u32_e32 v96, 10, v0
	v_mad_i64_i32 v[98:99], s[18:19], v96, s89, v[4:5]
	global_load_dword v69, v[98:99], off
	v_add_u32_e32 v96, 12, v0
	v_mad_i64_i32 v[98:99], s[18:19], v96, s89, v[4:5]
	global_load_dword v70, v[98:99], off
	v_add_u32_e32 v96, 14, v0
	v_mad_i64_i32 v[98:99], s[18:19], v96, s89, v[4:5]
	global_load_dword v71, v[98:99], off
	v_add_u32_e32 v96, 16, v0
	v_mad_i64_i32 v[98:99], s[18:19], v96, s89, v[4:5]
	global_load_dword v72, v[98:99], off
	v_add_u32_e32 v96, 18, v0
	v_mad_i64_i32 v[98:99], s[18:19], v96, s89, v[4:5]
	global_load_dword v73, v[98:99], off
	v_add_u32_e32 v96, 20, v0
	v_mad_i64_i32 v[98:99], s[18:19], v96, s89, v[4:5]
	global_load_dword v74, v[98:99], off
	v_add_u32_e32 v96, 22, v0
	v_mad_i64_i32 v[98:99], s[18:19], v96, s89, v[4:5]
	global_load_dword v75, v[98:99], off
	v_add_u32_e32 v96, 24, v0
	v_mad_i64_i32 v[98:99], s[18:19], v96, s89, v[4:5]
	global_load_dword v76, v[98:99], off
	v_add_u32_e32 v96, 26, v0
	v_mad_i64_i32 v[98:99], s[18:19], v96, s89, v[4:5]
	global_load_dword v77, v[98:99], off
	v_add_u32_e32 v96, 28, v0
	v_mad_i64_i32 v[98:99], s[18:19], v96, s89, v[4:5]
	global_load_dword v78, v[98:99], off
	v_add_u32_e32 v96, 30, v0
	v_mad_i64_i32 v[98:99], s[18:19], v96, s89, v[4:5]
	global_load_dword v79, v[98:99], off
	v_add_u32_e32 v96, 32, v0
	v_mad_i64_i32 v[98:99], s[18:19], v96, s89, v[4:5]
	global_load_dword v80, v[98:99], off
	v_add_u32_e32 v96, 34, v0
	v_mad_i64_i32 v[98:99], s[18:19], v96, s89, v[4:5]
	global_load_dword v81, v[98:99], off
	v_add_u32_e32 v96, 36, v0
	v_mad_i64_i32 v[98:99], s[18:19], v96, s89, v[4:5]
	global_load_dword v82, v[98:99], off
	v_add_u32_e32 v96, 38, v0
	v_mad_i64_i32 v[98:99], s[18:19], v96, s89, v[4:5]
	global_load_dword v83, v[98:99], off
	v_add_u32_e32 v96, 40, v0
	v_mad_i64_i32 v[98:99], s[18:19], v96, s89, v[4:5]
	global_load_dword v84, v[98:99], off
	v_add_u32_e32 v96, 42, v0
	v_mad_i64_i32 v[98:99], s[18:19], v96, s89, v[4:5]
	global_load_dword v85, v[98:99], off
	v_add_u32_e32 v96, 44, v0
	v_mad_i64_i32 v[98:99], s[18:19], v96, s89, v[4:5]
	global_load_dword v86, v[98:99], off
	v_add_u32_e32 v96, 46, v0
	v_mad_i64_i32 v[98:99], s[18:19], v96, s89, v[4:5]
	global_load_dword v87, v[98:99], off
	v_add_u32_e32 v96, 48, v0
	v_mad_i64_i32 v[98:99], s[18:19], v96, s89, v[4:5]
	global_load_dword v88, v[98:99], off
	v_add_u32_e32 v96, 50, v0
	v_mad_i64_i32 v[98:99], s[18:19], v96, s89, v[4:5]
	global_load_dword v89, v[98:99], off
	v_add_u32_e32 v96, 52, v0
	v_mad_i64_i32 v[98:99], s[18:19], v96, s89, v[4:5]
	global_load_dword v90, v[98:99], off
	v_add_u32_e32 v96, 54, v0
	v_mad_i64_i32 v[98:99], s[18:19], v96, s89, v[4:5]
	global_load_dword v91, v[98:99], off
	v_add_u32_e32 v96, 56, v0
	v_mad_i64_i32 v[98:99], s[18:19], v96, s89, v[4:5]
	global_load_dword v92, v[98:99], off
	v_add_u32_e32 v96, 58, v0
	v_mad_i64_i32 v[98:99], s[18:19], v96, s89, v[4:5]
	global_load_dword v93, v[98:99], off
	v_add_u32_e32 v96, 60, v0
	v_mad_i64_i32 v[98:99], s[18:19], v96, s89, v[4:5]
	global_load_dword v94, v[98:99], off
	v_add_u32_e32 v96, 62, v0
	v_mad_i64_i32 v[98:99], s[18:19], v96, s89, v[4:5]
	global_load_dword v95, v[98:99], off
	s_branch .Ltr615_w
.Ltr615_zero:
	v_mov_b32_e32 v64, 0
	v_mov_b32_e32 v65, 0
	v_mov_b32_e32 v66, 0
	v_mov_b32_e32 v67, 0
	v_mov_b32_e32 v68, 0
	v_mov_b32_e32 v69, 0
	v_mov_b32_e32 v70, 0
	v_mov_b32_e32 v71, 0
	v_mov_b32_e32 v72, 0
	v_mov_b32_e32 v73, 0
	v_mov_b32_e32 v74, 0
	v_mov_b32_e32 v75, 0
	v_mov_b32_e32 v76, 0
	v_mov_b32_e32 v77, 0
	v_mov_b32_e32 v78, 0
	v_mov_b32_e32 v79, 0
	v_mov_b32_e32 v80, 0
	v_mov_b32_e32 v81, 0
	v_mov_b32_e32 v82, 0
	v_mov_b32_e32 v83, 0
	v_mov_b32_e32 v84, 0
	v_mov_b32_e32 v85, 0
	v_mov_b32_e32 v86, 0
	v_mov_b32_e32 v87, 0
	v_mov_b32_e32 v88, 0
	v_mov_b32_e32 v89, 0
	v_mov_b32_e32 v90, 0
	v_mov_b32_e32 v91, 0
	v_mov_b32_e32 v92, 0
	v_mov_b32_e32 v93, 0
	v_mov_b32_e32 v94, 0
	v_mov_b32_e32 v95, 0
.Ltr615_w:
	s_waitcnt vmcnt(0)
	ds_write_b32 v3, v64
	ds_write_b32 v3, v65 offset:264
	ds_write_b32 v3, v66 offset:528
	ds_write_b32 v3, v67 offset:792
	ds_write_b32 v3, v68 offset:1056
	ds_write_b32 v3, v69 offset:1320
	ds_write_b32 v3, v70 offset:1584
	ds_write_b32 v3, v71 offset:1848
	ds_write_b32 v3, v72 offset:2112
	ds_write_b32 v3, v73 offset:2376
	ds_write_b32 v3, v74 offset:2640
	ds_write_b32 v3, v75 offset:2904
	ds_write_b32 v3, v76 offset:3168
	ds_write_b32 v3, v77 offset:3432
	ds_write_b32 v3, v78 offset:3696
	ds_write_b32 v3, v79 offset:3960
	ds_write_b32 v3, v80 offset:4224
	ds_write_b32 v3, v81 offset:4488
	ds_write_b32 v3, v82 offset:4752
	ds_write_b32 v3, v83 offset:5016
	ds_write_b32 v3, v84 offset:5280
	ds_write_b32 v3, v85 offset:5544
	ds_write_b32 v3, v86 offset:5808
	ds_write_b32 v3, v87 offset:6072
	ds_write_b32 v3, v88 offset:6336
	ds_write_b32 v3, v89 offset:6600
	ds_write_b32 v3, v90 offset:6864
	ds_write_b32 v3, v91 offset:7128
	ds_write_b32 v3, v92 offset:7392
	ds_write_b32 v3, v93 offset:7656
	ds_write_b32 v3, v94 offset:7920
	ds_write_b32 v3, v95 offset:8184
	s_branch .LBB0_612
